# main GQA k-tile loop: K fragments prefetched before the QK MFMAs, V fragments read during the softmax (registers avoiding the live lam_init / queue state)
# baseline (speedup 1.0000x reference)
; template <int D>
; DI void attn_pass(const bfr* __restrict__ P, int b, int tq_wave, int qcol, int kcol, int vcol, int key0, int nkt, char* smem, f32x16 (&o)[2]) {
;     ...
;     __syncthreads();
;     if (kt + 1 < nkt) {
;       const bfr* Pn = Pb + (size_t)(kt + 1) * 64 * PW;
;       { int c = gt, row = c >> 3, kc = c & 7; kreg[0] = *(const u32x4*)(Pn + (size_t)row * PW + kcol + kc * 8); vreg[0] = *(const u32x4*)(Pn + (size_t)row * PW + vcol + kc * 8); }
;     }
;     f32x16 s[2];
; #pragma unroll
;     for (int t2 = 0; t2 < 2; ++t2) {
; #pragma unroll
;       for (int i = 0; i < 16; ++i) s[t2][i] = 0.f;
; #pragma unroll
;       for (int ks = 0; ks < KS; ++ks) {
;         bf16x8 a = *(const bf16x8*)(sK + (t2 * 32 + r) * KP + ks * 16 + h * 8);
;         s[t2] = MFMA32(a, qf[ks], s[t2]);
;       }
;     }
;     float mx = s[0][0];
; #pragma unroll
;     for (int i = 0; i < 16; ++i) { mx = fmaxf(mx, s[0][i]); mx = fmaxf(mx, s[1][i]); }
;     mx = fmaxf(mx, __shfl_xor(mx, 32));
;     float mnew = fmaxf(mrun, mx);
;     float alpha = __builtin_amdgcn_exp2f(mrun - mnew);
;     mrun = mnew;
;     float ps = 0.f;
; #pragma unroll
;     for (int i = 0; i < 16; ++i) {
;       s[0][i] = __builtin_amdgcn_exp2f(s[0][i] - mnew); ps += s[0][i];
;       s[1][i] = __builtin_amdgcn_exp2f(s[1][i] - mnew); ps += s[1][i];
;     }
;     lsum = lsum * alpha + ps;
; #pragma unroll
;     for (int i = 0; i < 16; ++i) { accO[0][i] *= alpha; accO[1][i] *= alpha; }
; #pragma unroll
;     for (int t2 = 0; t2 < 2; ++t2)
; #pragma unroll
;       for (int j = 0; j < 2; ++j) {
;         unsigned pk[4];
; #pragma unroll
;         for (int e = 0; e < 4; ++e) pk[e] = pack2(s[t2][8 * j + 2 * e], s[t2][8 * j + 2 * e + 1]);
;         u32x4 pku = {pk[0], pk[1], pk[2], pk[3]};
;         bf16x8 pf = __builtin_bit_cast(bf16x8, pku);
; #pragma unroll
;         for (int dt = 0; dt < 2; ++dt) {
;           const int vsw = (((dt * 32 + r) >> 3) & 7) << 3;
;           const bfr* vrow = sV + (dt * 32 + r) * 72;
;           s16x4 lo = *(const s16x4*)(vrow + ((t2 * 32 + 16 * j + 4 * h) ^ vsw));
;           s16x4 hi = *(const s16x4*)(vrow + ((t2 * 32 + 16 * j + 4 * h + 8) ^ vsw));
;           bf16x8 vf = __builtin_shufflevector(lo, hi, 0, 1, 2, 3, 4, 5, 6, 7);
;           accO[dt] = MFMA32(vf, pf, accO[dt]);
;         }
;       }
.LBB0_412:
	s_bitcmp1_b32 s8, 0
	s_cselect_b32 s9, 0x4800, 0
	s_add_i32 s9, s9, 0
	v_add3_u32 v32, s9, v115, v90
	v_add_u32_e32 v121, s9, v114
	v_mov_b32_e32 v120, v113
	s_waitcnt vmcnt(1)
	ds_write_b128 v32, v[84:87]
	v_add3_u32 v32, s9, v117, v118
	v_add3_u32 v33, s9, v118, v117
	v_add_u32_e32 v113, v121, v152
	s_waitcnt vmcnt(0)
	ds_write_b16 v32, v80 offset:9216
	ds_write_b16_d16_hi v33, v80 offset:9360
	ds_write_b16 v32, v81 offset:9504
	ds_write_b16_d16_hi v33, v81 offset:9648
	ds_write_b16 v32, v82 offset:9792
	ds_write_b16_d16_hi v33, v82 offset:9936
	ds_write_b16 v32, v83 offset:10080
	ds_write_b16_d16_hi v33, v83 offset:10224
	s_waitcnt lgkmcnt(0)
	s_barrier
	global_load_dwordx4 v[84:87], v[92:93], off
	global_load_dwordx4 v[80:83], v[94:95], off
	ds_read_b128 v[126:129], v113
	ds_read_b128 v[130:133], v113 offset:32
	ds_read_b128 v[134:137], v113 offset:64
	ds_read_b128 v[138:141], v113 offset:96
	ds_read_b128 v[142:145], v113 offset:4608
	ds_read_b128 v[146:149], v113 offset:4640
	ds_read_b128 v[156:159], v113 offset:4672
	ds_read_b128 v[164:167], v113 offset:4704
	v_mov_b32_e32 v96, v119
	s_waitcnt lgkmcnt(7)
	v_mfma_f32_32x32x16_bf16 v[32:47], v[126:129], v[76:79], 0
	s_add_i32 s8, s8, 1
	s_waitcnt lgkmcnt(6)
	v_mfma_f32_32x32x16_bf16 v[32:47], v[130:133], v[72:75], v[32:47]
	v_lshl_add_u64 v[92:93], v[92:93], 0, s[10:11]
	s_waitcnt lgkmcnt(5)
	v_mfma_f32_32x32x16_bf16 v[32:47], v[134:137], v[68:71], v[32:47]
	v_lshl_add_u64 v[94:95], v[94:95], 0, s[10:11]
	s_waitcnt lgkmcnt(4)
	v_mfma_f32_32x32x16_bf16 v[32:47], v[138:141], v[64:67], v[32:47]
	s_cmp_lg_u32 s8, 35
	s_waitcnt lgkmcnt(3)
	v_mfma_f32_32x32x16_bf16 v[48:63], v[142:145], v[76:79], 0
	s_waitcnt lgkmcnt(2)
	v_mfma_f32_32x32x16_bf16 v[48:63], v[146:149], v[72:75], v[48:63]
	s_waitcnt lgkmcnt(1)
	v_mfma_f32_32x32x16_bf16 v[48:63], v[156:159], v[68:71], v[48:63]
	s_waitcnt lgkmcnt(0)
	v_mfma_f32_32x32x16_bf16 v[48:63], v[164:167], v[64:67], v[48:63]
	v_add_u32_e32 v154, s9, v116
	v_lshl_add_u32 v168, v112, 1, v121
	v_lshl_add_u32 v169, v111, 1, v121
	v_lshl_add_u32 v170, v110, 1, v154
	v_lshl_add_u32 v171, v109, 1, v154
	v_lshl_add_u32 v172, v108, 1, v121
	v_lshl_add_u32 v173, v107, 1, v121
	v_lshl_add_u32 v174, v106, 1, v154
	v_lshl_add_u32 v175, v105, 1, v154
	v_lshl_add_u32 v176, v104, 1, v121
	v_lshl_add_u32 v177, v103, 1, v154
	v_lshl_add_u32 v178, v102, 1, v154
	v_lshl_add_u32 v179, v100, 1, v121
	v_lshl_add_u32 v180, v101, 1, v121
	v_lshl_add_u32 v181, v99, 1, v154
	v_lshl_add_u32 v160, v98, 1, v154
	v_max_f32_e32 v119, v32, v32
	v_max_f32_e32 v113, v48, v48
	v_max_f32_e32 v113, v119, v113
	v_max3_f32 v113, v113, v33, v49
	v_max3_f32 v113, v113, v34, v50
	v_max3_f32 v113, v113, v35, v51
	v_max3_f32 v113, v113, v36, v52
	v_max3_f32 v113, v113, v37, v53
	v_max3_f32 v113, v113, v38, v54
	v_max3_f32 v113, v113, v39, v55
	v_max3_f32 v113, v113, v40, v56
	v_max3_f32 v113, v113, v41, v57
	v_max3_f32 v113, v113, v42, v58
	v_max3_f32 v113, v113, v43, v59
	v_max3_f32 v113, v113, v44, v60
	v_max3_f32 v113, v113, v45, v61
	v_max3_f32 v113, v113, v46, v62
	v_max3_f32 v113, v113, v47, v63
	ds_bpermute_b32 v119, v91, v113
	s_waitcnt lgkmcnt(0)
	ds_read_b64 v[126:127], v168 offset:9216
	ds_read_b64 v[128:129], v169 offset:9216
	ds_read_b64 v[130:131], v170 offset:9216
	ds_read_b64 v[132:133], v171 offset:9216
	ds_read_b64 v[134:135], v172 offset:9216
	ds_read_b64 v[136:137], v173 offset:9216
	ds_read_b64 v[138:139], v174 offset:9216
	ds_read_b64 v[140:141], v175 offset:9216
	v_max3_f32 v119, v96, v113, v119
	v_sub_f32_e32 v32, v32, v119
	v_sub_f32_e32 v38, v38, v119
	v_exp_f32_e32 v32, v32
	v_sub_f32_e32 v48, v48, v119
	v_sub_f32_e32 v36, v36, v119
	v_exp_f32_e32 v124, v38
	v_sub_f32_e32 v38, v54, v119
	v_exp_f32_e32 v48, v48
	v_sub_f32_e32 v33, v33, v119
	v_exp_f32_e32 v122, v36
	v_sub_f32_e32 v36, v52, v119
	v_exp_f32_e32 v52, v38
	v_sub_f32_e32 v38, v39, v119
	v_exp_f32_e32 v33, v33
	v_sub_f32_e32 v49, v49, v119
	v_sub_f32_e32 v37, v37, v119
	v_exp_f32_e32 v125, v38
	v_sub_f32_e32 v38, v55, v119
	v_exp_f32_e32 v49, v49
	v_sub_f32_e32 v34, v34, v119
	v_exp_f32_e32 v123, v37
	v_sub_f32_e32 v37, v53, v119
	v_exp_f32_e32 v53, v38
	v_sub_f32_e32 v38, v40, v119
	v_sub_f32_e32 v40, v42, v119
	v_sub_f32_e32 v42, v44, v119
	v_exp_f32_e32 v34, v34
	v_sub_f32_e32 v50, v50, v119
	v_exp_f32_e32 v54, v38
	v_sub_f32_e32 v38, v56, v119
	v_exp_f32_e32 v56, v40
	v_sub_f32_e32 v40, v58, v119
	v_exp_f32_e32 v58, v42
	v_sub_f32_e32 v42, v60, v119
	s_waitcnt lgkmcnt(4)
; #define MFMA32(a, b, c) __builtin_amdgcn_mfma_f32_32x32x16_bf16((a), (b), (c), 0, 0, 0)
; DI unsigned pack2(float a, float b) { unsigned r; asm volatile("v_cvt_pk_bf16_f32 %0, %1, %2" : "=v"(r) : "v"(a), "v"(b)); return r; }
; template <int D>
; DI void attn_pass(const bfr* __restrict__ P, int b, int tq_wave, int qcol, int kcol, int vcol, int key0, int nkt, char* smem, f32x16 (&o)[2]) {
;     ...
;     float mx = s[0][0];
; #pragma unroll
;     for (int i = 0; i < 16; ++i) { mx = fmaxf(mx, s[0][i]); mx = fmaxf(mx, s[1][i]); }
;     mx = fmaxf(mx, __shfl_xor(mx, 32));
;     float mnew = fmaxf(mrun, mx);
;     float alpha = __builtin_amdgcn_exp2f(mrun - mnew);
;     mrun = mnew;
;     float ps = 0.f;
; #pragma unroll
;     for (int i = 0; i < 16; ++i) {
;       s[0][i] = __builtin_amdgcn_exp2f(s[0][i] - mnew); ps += s[0][i];
;       s[1][i] = __builtin_amdgcn_exp2f(s[1][i] - mnew); ps += s[1][i];
;     }
;     lsum = lsum * alpha + ps;
; #pragma unroll
;     for (int i = 0; i < 16; ++i) { accO[0][i] *= alpha; accO[1][i] *= alpha; }
; #pragma unroll
;     for (int t2 = 0; t2 < 2; ++t2)
; #pragma unroll
;       for (int j = 0; j < 2; ++j) {
;         unsigned pk[4];
; #pragma unroll
;         for (int e = 0; e < 4; ++e) pk[e] = pack2(s[t2][8 * j + 2 * e], s[t2][8 * j + 2 * e + 1]);
;         u32x4 pku = {pk[0], pk[1], pk[2], pk[3]};
;         bf16x8 pf = __builtin_bit_cast(bf16x8, pku);
; #pragma unroll
;         for (int dt = 0; dt < 2; ++dt) {
;           const int vsw = (((dt * 32 + r) >> 3) & 7) << 3;
;           const bfr* vrow = sV + (dt * 32 + r) * 72;
;           s16x4 lo = *(const s16x4*)(vrow + ((t2 * 32 + 16 * j + 4 * h) ^ vsw));
;           s16x4 hi = *(const s16x4*)(vrow + ((t2 * 32 + 16 * j + 4 * h + 8) ^ vsw));
;           bf16x8 vf = __builtin_shufflevector(lo, hi, 0, 1, 2, 3, 4, 5, 6, 7);
;           accO[dt] = MFMA32(vf, pf, accO[dt]);
;         }
;       }
	ds_read_b64 v[142:143], v168 offset:9280
	ds_read_b64 v[144:145], v176 offset:9216
	ds_read_b64 v[146:147], v177 offset:9216
	ds_read_b64 v[148:149], v178 offset:9216
	ds_read_b64 v[156:157], v179 offset:9216
	ds_read_b64 v[158:159], v180 offset:9216
	ds_read_b64 v[164:165], v181 offset:9216
	ds_read_b64 v[166:167], v160 offset:9216
	v_add_f32_e32 v60, 0, v32
	v_exp_f32_e32 v50, v50
	v_sub_f32_e32 v35, v35, v119
	v_add_f32_e32 v60, v48, v60
	v_exp_f32_e32 v35, v35
	v_sub_f32_e32 v51, v51, v119
	v_add_f32_e32 v60, v33, v60
	v_exp_f32_e32 v51, v51
	v_add_f32_e32 v60, v49, v60
	v_add_f32_e32 v60, v34, v60
	v_exp_f32_e32 v36, v36
	v_add_f32_e32 v60, v50, v60
	v_add_f32_e32 v60, v35, v60
	v_exp_f32_e32 v37, v37
	v_add_f32_e32 v60, v51, v60
	v_add_f32_e32 v60, v122, v60
	v_add_f32_e32 v60, v36, v60
	v_add_f32_e32 v60, v123, v60
	v_add_f32_e32 v60, v37, v60
	v_add_f32_e32 v60, v124, v60
	v_exp_f32_e32 v38, v38
	v_sub_f32_e32 v39, v41, v119
	v_add_f32_e32 v60, v52, v60
	v_exp_f32_e32 v55, v39
	v_sub_f32_e32 v39, v57, v119
	v_add_f32_e32 v60, v125, v60
	v_exp_f32_e32 v39, v39
	v_add_f32_e32 v60, v53, v60
	v_add_f32_e32 v60, v54, v60
	v_exp_f32_e32 v40, v40
	v_sub_f32_e32 v41, v43, v119
	v_add_f32_e32 v60, v38, v60
	v_exp_f32_e32 v57, v41
	v_sub_f32_e32 v41, v59, v119
	v_add_f32_e32 v60, v55, v60
	v_exp_f32_e32 v41, v41
	v_add_f32_e32 v60, v39, v60
	v_add_f32_e32 v60, v56, v60
	v_exp_f32_e32 v42, v42
	v_sub_f32_e32 v43, v45, v119
	v_add_f32_e32 v60, v40, v60
	v_exp_f32_e32 v59, v43
	v_sub_f32_e32 v43, v61, v119
	v_add_f32_e32 v60, v57, v60
	v_exp_f32_e32 v43, v43
	v_sub_f32_e32 v44, v46, v119
	v_add_f32_e32 v60, v41, v60
	v_exp_f32_e32 v46, v44
	v_sub_f32_e32 v44, v62, v119
	v_add_f32_e32 v60, v58, v60
	v_exp_f32_e32 v44, v44
	v_sub_f32_e32 v45, v47, v119
	v_add_f32_e32 v60, v42, v60
	v_exp_f32_e32 v47, v45
	v_sub_f32_e32 v45, v63, v119
	v_add_f32_e32 v60, v59, v60
	v_exp_f32_e32 v45, v45
	v_add_f32_e32 v60, v43, v60
	v_add_f32_e32 v60, v46, v60
	v_add_f32_e32 v60, v44, v60
	v_add_f32_e32 v60, v47, v60
	v_add_f32_e32 v113, v45, v60
	v_cvt_pk_bf16_f32 v32, v32, v33
	v_cvt_pk_bf16_f32 v33, v34, v35
	v_cvt_pk_bf16_f32 v34, v122, v123
	v_cvt_pk_bf16_f32 v35, v124, v125
	v_sub_f32_e32 v96, v96, v119
	v_exp_f32_e32 v96, v96
	s_nop 1
	v_pk_mul_f32 v[30:31], v[30:31], v[96:97] op_sel_hi:[1,0]
	v_pk_mul_f32 v[28:29], v[28:29], v[96:97] op_sel_hi:[1,0]
	v_pk_mul_f32 v[26:27], v[26:27], v[96:97] op_sel_hi:[1,0]
	v_pk_mul_f32 v[24:25], v[24:25], v[96:97] op_sel_hi:[1,0]
	v_pk_mul_f32 v[22:23], v[22:23], v[96:97] op_sel_hi:[1,0]
	v_pk_mul_f32 v[20:21], v[20:21], v[96:97] op_sel_hi:[1,0]
	v_pk_mul_f32 v[18:19], v[18:19], v[96:97] op_sel_hi:[1,0]
	v_pk_mul_f32 v[16:17], v[16:17], v[96:97] op_sel_hi:[1,0]
	v_pk_mul_f32 v[14:15], v[14:15], v[96:97] op_sel_hi:[1,0]
	v_pk_mul_f32 v[12:13], v[12:13], v[96:97] op_sel_hi:[1,0]
	s_waitcnt lgkmcnt(0)
	v_mfma_f32_32x32x16_bf16 v[16:31], v[126:129], v[32:35], v[16:31]
	v_mul_f32_e64 v10, v10, v96
	v_mul_f32_e64 v11, v11, v96
	v_pk_mul_f32 v[8:9], v[8:9], v[96:97] op_sel_hi:[1,0]
	v_pk_mul_f32 v[6:7], v[6:7], v[96:97] op_sel_hi:[1,0]
	v_pk_mul_f32 v[4:5], v[4:5], v[96:97] op_sel_hi:[1,0]
	v_pk_mul_f32 v[2:3], v[2:3], v[96:97] op_sel_hi:[1,0]
	v_pk_mul_f32 v[0:1], v[0:1], v[96:97] op_sel_hi:[1,0]
	v_fmac_f32_e32 v113, v120, v96
	s_nop 1
	v_mfma_f32_32x32x16_bf16 v[0:15], v[130:133], v[32:35], v[0:15]
	v_cvt_pk_bf16_f32 v32, v54, v55
	v_cvt_pk_bf16_f32 v33, v56, v57
	v_cvt_pk_bf16_f32 v34, v58, v59
	v_cvt_pk_bf16_f32 v35, v46, v47
	s_nop 1
	v_mfma_f32_32x32x16_bf16 v[16:31], v[134:137], v[32:35], v[16:31]
	s_nop 1
	v_mfma_f32_32x32x16_bf16 v[0:15], v[138:141], v[32:35], v[0:15]
	v_cvt_pk_bf16_f32 v32, v48, v49
	v_cvt_pk_bf16_f32 v33, v50, v51
	v_cvt_pk_bf16_f32 v34, v36, v37
	v_cvt_pk_bf16_f32 v35, v52, v53
	s_nop 1
	v_mfma_f32_32x32x16_bf16 v[16:31], v[142:145], v[32:35], v[16:31]
	s_nop 1
	v_mfma_f32_32x32x16_bf16 v[0:15], v[146:149], v[32:35], v[0:15]
	v_cvt_pk_bf16_f32 v32, v38, v39
	v_cvt_pk_bf16_f32 v33, v40, v41
	v_cvt_pk_bf16_f32 v34, v42, v43
	v_cvt_pk_bf16_f32 v35, v44, v45
	s_nop 1
	v_mfma_f32_32x32x16_bf16 v[16:31], v[156:159], v[32:35], v[16:31]
	s_nop 1
	v_mfma_f32_32x32x16_bf16 v[0:15], v[164:167], v[32:35], v[0:15]
	s_cbranch_scc1 .LBB0_412
	v_add3_u32 v32, 0, v115, v90
	s_waitcnt vmcnt(1)
	ds_write_b128 v32, v[84:87] offset:18432
	v_add3_u32 v32, 0, v117, v118
	v_add3_u32 v33, 0, v118, v117
	s_waitcnt vmcnt(0)
	ds_write_b16 v32, v80 offset:27648
	ds_write_b16_d16_hi v33, v80 offset:27792
	ds_write_b16 v32, v81 offset:27936
	ds_write_b16_d16_hi v33, v81 offset:28080
	ds_write_b16 v32, v82 offset:28224
	ds_write_b16_d16_hi v33, v82 offset:28368
	ds_write_b16 v32, v83 offset:28512
	ds_write_b16_d16_hi v33, v83 offset:28656
	v_add_u32_e32 v80, 0, v114
	v_add_u32_e32 v81, v80, v152
	s_waitcnt lgkmcnt(0)
	s_barrier
; #define MFMA32(a, b, c) __builtin_amdgcn_mfma_f32_32x32x16_bf16((a), (b), (c), 0, 0, 0)
; DI unsigned pack2(float a, float b) { unsigned r; asm volatile("v_cvt_pk_bf16_f32 %0, %1, %2" : "=v"(r) : "v"(a), "v"(b)); return r; }
; template <int D>
; DI void attn_pass(const bfr* __restrict__ P, int b, int tq_wave, int qcol, int kcol, int vcol, int key0, int nkt, char* smem, f32x16 (&o)[2]) {
;     ...
;     f32x16 s[2];
; #pragma unroll
;     for (int t2 = 0; t2 < 2; ++t2) {
; #pragma unroll
;       for (int i = 0; i < 16; ++i) s[t2][i] = 0.f;
; #pragma unroll
;       for (int ks = 0; ks < KS; ++ks) {
;         bf16x8 a = *(const bf16x8*)(sK + (t2 * 32 + r) * KP + ks * 16 + h * 8);
;         s[t2] = MFMA32(a, qf[ks], s[t2]);
;       }
;     }
;     float mx = s[0][0];
; #pragma unroll
;     for (int i = 0; i < 16; ++i) { mx = fmaxf(mx, s[0][i]); mx = fmaxf(mx, s[1][i]); }
;     mx = fmaxf(mx, __shfl_xor(mx, 32));
;     float mnew = fmaxf(mrun, mx);
;     float alpha = __builtin_amdgcn_exp2f(mrun - mnew);
;     mrun = mnew;
;     float ps = 0.f;
; #pragma unroll
;     for (int i = 0; i < 16; ++i) {
;       s[0][i] = __builtin_amdgcn_exp2f(s[0][i] - mnew); ps += s[0][i];
;       s[1][i] = __builtin_amdgcn_exp2f(s[1][i] - mnew); ps += s[1][i];
;     }
;     lsum = lsum * alpha + ps;
; #pragma unroll
;     for (int i = 0; i < 16; ++i) { accO[0][i] *= alpha; accO[1][i] *= alpha; }
; #pragma unroll
;     for (int t2 = 0; t2 < 2; ++t2)
; #pragma unroll
;       for (int j = 0; j < 2; ++j) {
;         unsigned pk[4];
; #pragma unroll
;         for (int e = 0; e < 4; ++e) pk[e] = pack2(s[t2][8 * j + 2 * e], s[t2][8 * j + 2 * e + 1]);
;         u32x4 pku = {pk[0], pk[1], pk[2], pk[3]};
;         bf16x8 pf = __builtin_bit_cast(bf16x8, pku);
; #pragma unroll
;         for (int dt = 0; dt < 2; ++dt) {
;           const int vsw = (((dt * 32 + r) >> 3) & 7) << 3;
;           const bfr* vrow = sV + (dt * 32 + r) * 72;
;           s16x4 lo = *(const s16x4*)(vrow + ((t2 * 32 + 16 * j + 4 * h) ^ vsw));
;           s16x4 hi = *(const s16x4*)(vrow + ((t2 * 32 + 16 * j + 4 * h + 8) ^ vsw));
;           bf16x8 vf = __builtin_shufflevector(lo, hi, 0, 1, 2, 3, 4, 5, 6, 7);
;           accO[dt] = MFMA32(vf, pf, accO[dt]);
;         }
;       }
	ds_read_b128 v[32:35], v81 offset:18432
	ds_read_b128 v[48:51], v81 offset:18464
	s_waitcnt lgkmcnt(1)
	v_mfma_f32_32x32x16_bf16 v[32:47], v[32:35], v[76:79], 0
	v_lshlrev_b32_e32 v152, 1, v88
	s_waitcnt lgkmcnt(0)
	v_mfma_f32_32x32x16_bf16 v[32:47], v[48:51], v[72:75], v[32:47]
	ds_read_b128 v[48:51], v81 offset:18496
	s_waitcnt lgkmcnt(0)
	v_mfma_f32_32x32x16_bf16 v[32:47], v[48:51], v[68:71], v[32:47]
	ds_read_b128 v[48:51], v81 offset:18528
	s_waitcnt lgkmcnt(0)
	v_mfma_f32_32x32x16_bf16 v[32:47], v[48:51], v[64:67], v[32:47]
	ds_read_b128 v[48:51], v81 offset:23040
	s_waitcnt lgkmcnt(0)
	v_mfma_f32_32x32x16_bf16 v[48:63], v[48:51], v[76:79], 0
	ds_read_b128 v[76:79], v81 offset:23072
	s_waitcnt lgkmcnt(0)
	v_mfma_f32_32x32x16_bf16 v[48:63], v[76:79], v[72:75], v[48:63]
	ds_read_b128 v[72:75], v81 offset:23104
	s_waitcnt lgkmcnt(0)
	v_mfma_f32_32x32x16_bf16 v[48:63], v[72:75], v[68:71], v[48:63]
	ds_read_b128 v[68:71], v81 offset:23136
	s_waitcnt lgkmcnt(0)
	v_mfma_f32_32x32x16_bf16 v[48:63], v[68:71], v[64:67], v[48:63]
	v_max_f32_e32 v65, v32, v32
	v_lshl_add_u32 v66, v112, 1, v80
	v_add_u32_e32 v67, 0x1200, v80
	s_nop 8
	v_max_f32_e32 v64, v48, v48
	v_max_f32_e32 v64, v65, v64
	v_max3_f32 v64, v64, v33, v49
	v_max3_f32 v64, v64, v34, v50
	v_max3_f32 v64, v64, v35, v51
	v_max3_f32 v64, v64, v36, v52
	v_max3_f32 v64, v64, v37, v53
	v_max3_f32 v64, v64, v38, v54
	v_max3_f32 v64, v64, v39, v55
	v_max3_f32 v64, v64, v40, v56
	v_max3_f32 v64, v64, v41, v57
	v_max3_f32 v64, v64, v42, v58
	v_max3_f32 v64, v64, v43, v59
	v_max3_f32 v64, v64, v44, v60
	v_max3_f32 v64, v64, v45, v61
	v_max3_f32 v64, v64, v46, v62
	v_max3_f32 v64, v64, v47, v63
	ds_bpermute_b32 v65, v91, v64
	s_waitcnt lgkmcnt(0)
	v_max3_f32 v65, v119, v64, v65
	v_sub_f32_e32 v64, v119, v65
	v_sub_f32_e32 v32, v32, v65
	v_exp_f32_e32 v64, v64
	v_exp_f32_e32 v32, v32
	v_sub_f32_e32 v48, v48, v65
	v_exp_f32_e32 v48, v48
	v_sub_f32_e32 v33, v33, v65
	v_exp_f32_e32 v33, v33
	v_sub_f32_e32 v49, v49, v65
	v_exp_f32_e32 v49, v49
	v_sub_f32_e32 v34, v34, v65
	v_exp_f32_e32 v34, v34
	v_sub_f32_e32 v50, v50, v65
	v_sub_f32_e32 v35, v35, v65
	v_sub_f32_e32 v51, v51, v65
	v_sub_f32_e32 v36, v36, v65
	v_sub_f32_e32 v52, v52, v65
	v_sub_f32_e32 v37, v37, v65
	v_sub_f32_e32 v53, v53, v65
	v_sub_f32_e32 v38, v38, v65
	v_sub_f32_e32 v54, v54, v65
	v_sub_f32_e32 v39, v39, v65
	v_sub_f32_e32 v55, v55, v65
	v_sub_f32_e32 v40, v40, v65
	v_sub_f32_e32 v56, v56, v65
	v_sub_f32_e32 v41, v41, v65
	v_sub_f32_e32 v57, v57, v65
	v_sub_f32_e32 v42, v42, v65
	v_sub_f32_e32 v58, v58, v65
	v_sub_f32_e32 v43, v43, v65
	v_sub_f32_e32 v59, v59, v65
	v_sub_f32_e32 v44, v44, v65
	v_sub_f32_e32 v60, v60, v65
	v_sub_f32_e32 v45, v45, v65
	v_sub_f32_e32 v61, v61, v65
	v_sub_f32_e32 v46, v46, v65
	v_sub_f32_e32 v62, v62, v65
	v_sub_f32_e32 v47, v47, v65
	v_sub_f32_e32 v63, v63, v65
	v_pk_mul_f32 v[30:31], v[30:31], v[64:65] op_sel_hi:[1,0]
	v_pk_mul_f32 v[28:29], v[28:29], v[64:65] op_sel_hi:[1,0]
	v_pk_mul_f32 v[26:27], v[26:27], v[64:65] op_sel_hi:[1,0]
	v_pk_mul_f32 v[24:25], v[24:25], v[64:65] op_sel_hi:[1,0]
	v_pk_mul_f32 v[22:23], v[22:23], v[64:65] op_sel_hi:[1,0]
	v_pk_mul_f32 v[20:21], v[20:21], v[64:65] op_sel_hi:[1,0]
	v_pk_mul_f32 v[18:19], v[18:19], v[64:65] op_sel_hi:[1,0]
	v_pk_mul_f32 v[16:17], v[16:17], v[64:65] op_sel_hi:[1,0]
	v_pk_mul_f32 v[14:15], v[14:15], v[64:65] op_sel_hi:[1,0]
	v_pk_mul_f32 v[12:13], v[12:13], v[64:65] op_sel_hi:[1,0]
	v_pk_mul_f32 v[10:11], v[10:11], v[64:65] op_sel_hi:[1,0]
	v_pk_mul_f32 v[8:9], v[8:9], v[64:65] op_sel_hi:[1,0]
	v_pk_mul_f32 v[6:7], v[6:7], v[64:65] op_sel_hi:[1,0]
	v_pk_mul_f32 v[4:5], v[4:5], v[64:65] op_sel_hi:[1,0]
	v_pk_mul_f32 v[2:3], v[2:3], v[64:65] op_sel_hi:[1,0]
	v_pk_mul_f32 v[0:1], v[0:1], v[64:65] op_sel_hi:[1,0]
	v_add_f32_e32 v65, 0, v32
	v_exp_f32_e32 v50, v50
	v_add_f32_e32 v65, v48, v65
	v_exp_f32_e32 v35, v35
	v_add_f32_e32 v65, v33, v65
	v_exp_f32_e32 v51, v51
	v_add_f32_e32 v65, v49, v65
	v_exp_f32_e32 v36, v36
	v_add_f32_e32 v65, v34, v65
	v_exp_f32_e32 v52, v52
	v_add_f32_e32 v65, v50, v65
	v_exp_f32_e32 v37, v37
	v_add_f32_e32 v65, v35, v65
	v_exp_f32_e32 v53, v53
	v_add_f32_e32 v65, v51, v65
	v_exp_f32_e32 v38, v38
	v_add_f32_e32 v65, v36, v65
	v_exp_f32_e32 v54, v54
	v_add_f32_e32 v65, v52, v65
	v_exp_f32_e32 v39, v39
	v_add_f32_e32 v65, v37, v65
	v_add_f32_e32 v65, v53, v65
	v_add_f32_e32 v65, v38, v65
	v_add_f32_e32 v65, v54, v65
	v_cvt_pk_bf16_f32 v32, v32, v33
	v_cvt_pk_bf16_f32 v33, v34, v35
	v_cvt_pk_bf16_f32 v34, v36, v37
	v_cvt_pk_bf16_f32 v35, v38, v39
	v_lshl_add_u32 v38, v111, 1, v80
	v_add_f32_e32 v65, v39, v65
	ds_read_b64 v[36:37], v66 offset:27648
	ds_read_b64 v[38:39], v38 offset:27648
	s_waitcnt lgkmcnt(0)
	v_mfma_f32_32x32x16_bf16 v[16:31], v[36:39], v[32:35], v[16:31]
	v_lshl_add_u32 v36, v110, 1, v67
	v_lshl_add_u32 v38, v109, 1, v67
	ds_read_b64 v[36:37], v36 offset:27648
	ds_read_b64 v[38:39], v38 offset:27648
	v_exp_f32_e32 v40, v40
	v_exp_f32_e32 v41, v41
	v_exp_f32_e32 v42, v42
	s_waitcnt lgkmcnt(0)
; #define MFMA32(a, b, c) __builtin_amdgcn_mfma_f32_32x32x16_bf16((a), (b), (c), 0, 0, 0)
; DI unsigned pack2(float a, float b) { unsigned r; asm volatile("v_cvt_pk_bf16_f32 %0, %1, %2" : "=v"(r) : "v"(a), "v"(b)); return r; }
; template <int D>
; DI void attn_pass(const bfr* __restrict__ P, int b, int tq_wave, int qcol, int kcol, int vcol, int key0, int nkt, char* smem, f32x16 (&o)[2]) {
;     ...
;     for (int i = 0; i < 16; ++i) { accO[0][i] *= alpha; accO[1][i] *= alpha; }
; #pragma unroll
;     for (int t2 = 0; t2 < 2; ++t2)
; #pragma unroll
;       for (int j = 0; j < 2; ++j) {
;         unsigned pk[4];
; #pragma unroll
;         for (int e = 0; e < 4; ++e) pk[e] = pack2(s[t2][8 * j + 2 * e], s[t2][8 * j + 2 * e + 1]);
;         u32x4 pku = {pk[0], pk[1], pk[2], pk[3]};
;         bf16x8 pf = __builtin_bit_cast(bf16x8, pku);
; #pragma unroll
;         for (int dt = 0; dt < 2; ++dt) {
;           const int vsw = (((dt * 32 + r) >> 3) & 7) << 3;
;           const bfr* vrow = sV + (dt * 32 + r) * 72;
;           s16x4 lo = *(const s16x4*)(vrow + ((t2 * 32 + 16 * j + 4 * h) ^ vsw));
;           s16x4 hi = *(const s16x4*)(vrow + ((t2 * 32 + 16 * j + 4 * h + 8) ^ vsw));
;           bf16x8 vf = __builtin_shufflevector(lo, hi, 0, 1, 2, 3, 4, 5, 6, 7);
;           accO[dt] = MFMA32(vf, pf, accO[dt]);
;         }
;       }
;   }
;   lsum += __shfl_xor(lsum, 32);
;   float inv = 1.f / lsum;
; #pragma unroll
;   for (int i = 0; i < 16; ++i) { o[0][i] = accO[0][i] * inv; o[1][i] = accO[1][i] * inv; }
; DI void store_o(bfr* O, int m, int colbase, int h, const f32x16 (&o)[2]) {
; #pragma unroll
;   for (int dt = 0; dt < 2; ++dt)
; #pragma unroll
;     for (int g4 = 0; g4 < 4; ++g4) {
;       int dv = dt * 32 + 8 * g4 + 4 * h;
;       uint2 pk; pk.x = pack2(o[dt][4 * g4], o[dt][4 * g4 + 1]); pk.y = pack2(o[dt][4 * g4 + 2], o[dt][4 * g4 + 3]);
;       *(uint2*)(O + (size_t)m * DM + colbase + dv) = pk;
;     }
	v_mfma_f32_32x32x16_bf16 v[0:15], v[36:39], v[32:35], v[0:15]
	v_lshl_add_u32 v36, v108, 1, v80
	v_lshl_add_u32 v38, v107, 1, v80
	v_exp_f32_e32 v43, v43
	v_exp_f32_e32 v44, v44
	v_exp_f32_e32 v45, v45
	v_exp_f32_e32 v46, v46
	v_exp_f32_e32 v47, v47
	v_cvt_pk_bf16_f32 v32, v40, v41
	v_cvt_pk_bf16_f32 v33, v42, v43
	v_cvt_pk_bf16_f32 v34, v44, v45
	v_cvt_pk_bf16_f32 v35, v46, v47
	ds_read_b64 v[36:37], v36 offset:27648
	ds_read_b64 v[38:39], v38 offset:27648
	s_waitcnt lgkmcnt(0)
	v_mfma_f32_32x32x16_bf16 v[16:31], v[36:39], v[32:35], v[16:31]
	v_lshl_add_u32 v36, v106, 1, v67
	v_lshl_add_u32 v38, v105, 1, v67
	ds_read_b64 v[36:37], v36 offset:27648
	ds_read_b64 v[38:39], v38 offset:27648
	v_exp_f32_e32 v55, v55
	v_exp_f32_e32 v56, v56
	v_exp_f32_e32 v57, v57
	s_waitcnt lgkmcnt(0)
	v_mfma_f32_32x32x16_bf16 v[0:15], v[36:39], v[32:35], v[0:15]
	v_lshl_add_u32 v38, v104, 1, v80
	v_cvt_pk_bf16_f32 v32, v48, v49
	v_cvt_pk_bf16_f32 v33, v50, v51
	v_cvt_pk_bf16_f32 v34, v52, v53
	v_cvt_pk_bf16_f32 v35, v54, v55
	ds_read_b64 v[36:37], v66 offset:27712
	ds_read_b64 v[38:39], v38 offset:27648
	s_waitcnt lgkmcnt(0)
	v_mfma_f32_32x32x16_bf16 v[16:31], v[36:39], v[32:35], v[16:31]
	v_lshl_add_u32 v36, v103, 1, v67
	v_lshl_add_u32 v38, v102, 1, v67
	ds_read_b64 v[36:37], v36 offset:27648
	ds_read_b64 v[38:39], v38 offset:27648
	v_exp_f32_e32 v58, v58
	v_exp_f32_e32 v59, v59
	v_exp_f32_e32 v60, v60
	s_waitcnt lgkmcnt(0)
	v_mfma_f32_32x32x16_bf16 v[0:15], v[36:39], v[32:35], v[0:15]
	v_lshl_add_u32 v36, v100, 1, v80
	v_lshl_add_u32 v38, v101, 1, v80
	v_exp_f32_e32 v61, v61
	v_exp_f32_e32 v62, v62
	v_exp_f32_e32 v63, v63
	v_cvt_pk_bf16_f32 v32, v56, v57
	v_cvt_pk_bf16_f32 v33, v58, v59
	v_cvt_pk_bf16_f32 v34, v60, v61
	v_cvt_pk_bf16_f32 v35, v62, v63
	ds_read_b64 v[36:37], v36 offset:27648
	ds_read_b64 v[38:39], v38 offset:27648
	v_add_f32_e32 v65, v55, v65
	v_add_f32_e32 v65, v40, v65
	v_add_f32_e32 v65, v56, v65
	v_add_f32_e32 v65, v41, v65
	v_add_f32_e32 v65, v57, v65
	v_add_f32_e32 v65, v42, v65
	v_add_f32_e32 v65, v58, v65
	v_add_f32_e32 v65, v43, v65
	v_add_f32_e32 v65, v59, v65
	s_waitcnt lgkmcnt(0)
	v_mfma_f32_32x32x16_bf16 v[16:31], v[36:39], v[32:35], v[16:31]
	v_lshl_add_u32 v36, v99, 1, v67
	v_lshl_add_u32 v38, v98, 1, v67
	v_add_f32_e32 v65, v44, v65
	ds_read_b64 v[36:37], v36 offset:27648
	ds_read_b64 v[38:39], v38 offset:27648
	v_add_f32_e32 v65, v60, v65
	v_add_f32_e32 v65, v45, v65
	v_add_f32_e32 v65, v61, v65
	v_add_f32_e32 v65, v46, v65
	v_add_f32_e32 v65, v62, v65
	v_add_f32_e32 v65, v47, v65
	v_add_f32_e32 v65, v63, v65
	v_fmac_f32_e32 v65, v113, v64
	s_waitcnt lgkmcnt(0)
	v_mfma_f32_32x32x16_bf16 v[0:15], v[36:39], v[32:35], v[0:15]
	ds_bpermute_b32 v32, v91, v65
	s_waitcnt lgkmcnt(0)
	v_add_f32_e32 v32, v65, v32
	v_div_scale_f32 v33, s[8:9], v32, v32, 1.0
	v_rcp_f32_e32 v34, v33
	s_load_dwordx4 s[8:11], s[0:1], 0x100
	s_waitcnt lgkmcnt(0)
	s_mov_b64 s[8:9], 0x2b7c700
	v_fma_f32 v35, -v33, v34, 1.0
	v_fmac_f32_e32 v34, v35, v34
	v_div_scale_f32 v35, vcc, 1.0, v32, 1.0
	v_mul_f32_e32 v36, v35, v34
	v_fma_f32 v37, -v33, v36, v35
	v_fmac_f32_e32 v36, v37, v34
	v_fma_f32 v33, -v33, v36, v35
	v_div_fmas_f32 v33, v33, v34, v36
	v_div_fixup_f32 v32, v33, v32, 1.0
	v_mul_f32_e32 v33, v0, v32
	v_and_or_b32 v0, v89, 31, v97
	v_mul_f32_e32 v34, v1, v32
	v_ashrrev_i32_e32 v1, 31, v0
	v_lshlrev_b64 v[0:1], 11, v[0:1]
	v_mul_f32_e32 v37, v4, v32
	v_lshl_add_u64 v[0:1], s[10:11], 0, v[0:1]
	v_lshrrev_b32_e32 v4, 2, v89
	v_lshl_add_u64 v[0:1], v[0:1], 0, v[152:153]
	v_and_b32_e32 v152, 8, v4
	v_lshl_add_u64 v[0:1], v[0:1], 0, v[152:153]
	v_mul_f32_e32 v38, v5, v32
	v_lshl_add_u64 v[4:5], v[0:1], 0, s[8:9]
	s_mov_b32 s8, 0x2b7c000
	v_add_co_u32_e32 v0, vcc, s8, v0
	v_mul_f32_e32 v16, v16, v32
	s_nop 0
	v_addc_co_u32_e32 v1, vcc, 0, v1, vcc
	v_mul_f32_e32 v17, v17, v32
	v_mul_f32_e32 v18, v18, v32
	v_mul_f32_e32 v35, v2, v32
	v_mul_f32_e32 v19, v19, v32
	v_mul_f32_e32 v36, v3, v32
	v_mul_f32_e32 v20, v20, v32
	v_mul_f32_e32 v21, v21, v32
	v_mul_f32_e32 v22, v22, v32
	v_mul_f32_e32 v23, v23, v32
	v_cvt_pk_bf16_f32 v2, v16, v17
	v_cvt_pk_bf16_f32 v3, v18, v19
	global_store_dwordx2 v[0:1], v[2:3], off offset:1792
	v_cvt_pk_bf16_f32 v0, v20, v21
	v_cvt_pk_bf16_f32 v1, v22, v23
	v_mul_f32_e32 v24, v24, v32
	v_mul_f32_e32 v25, v25, v32
	v_mul_f32_e32 v26, v26, v32
	v_mul_f32_e32 v27, v27, v32
	global_store_dwordx2 v[4:5], v[0:1], off offset:16
	v_cvt_pk_bf16_f32 v0, v24, v25
	v_cvt_pk_bf16_f32 v1, v26, v27
	v_mul_f32_e32 v28, v28, v32
	v_mul_f32_e32 v29, v29, v32
	v_mul_f32_e32 v30, v30, v32
	v_mul_f32_e32 v31, v31, v32
	global_store_dwordx2 v[4:5], v[0:1], off offset:32
	v_cvt_pk_bf16_f32 v0, v28, v29
	v_cvt_pk_bf16_f32 v1, v30, v31
	global_store_dwordx2 v[4:5], v[0:1], off offset:48
	v_cvt_pk_bf16_f32 v0, v33, v34
	v_cvt_pk_bf16_f32 v1, v35, v36
	v_mul_f32_e32 v6, v6, v32
	v_mul_f32_e32 v7, v7, v32
	global_store_dwordx2 v[4:5], v[0:1], off offset:64
	v_cvt_pk_bf16_f32 v0, v37, v38
	v_cvt_pk_bf16_f32 v1, v6, v7
	v_mul_f32_e32 v8, v8, v32
	v_mul_f32_e32 v9, v9, v32
	v_mul_f32_e32 v10, v10, v32
	v_mul_f32_e32 v11, v11, v32
	global_store_dwordx2 v[4:5], v[0:1], off offset:80
	v_cvt_pk_bf16_f32 v0, v8, v9
	v_cvt_pk_bf16_f32 v1, v10, v11
	v_mul_f32_e32 v12, v12, v32
	v_mul_f32_e32 v13, v13, v32
	v_mul_f32_e32 v14, v14, v32
	v_mul_f32_e32 v15, v15, v32
	global_store_dwordx2 v[4:5], v[0:1], off offset:96
	v_cvt_pk_bf16_f32 v0, v12, v13
	v_cvt_pk_bf16_f32 v1, v14, v15
	global_store_dwordx2 v[4:5], v[0:1], off offset:112
